# attention loop: the two no-op s_setprio 0 per tile removed (on top of trimmed GEMM loops)
# baseline (speedup 1.0000x reference)
; __device__ __forceinline__ void qkt(f32x16& p0, f32x16& p1, const unsigned char* Ks, const i32x8* qr, int r32, int hi) {
;   p0 = f32x16{}; p1 = f32x16{};
; #pragma unroll
;   for (int m = 0; m < 3; ++m) { const int cb = m * 64 + hi * 32;
;     const u32x4 a0 = *reinterpret_cast<const u32x4*>(Ks + KSWZ(r32, cb)), a1 = *reinterpret_cast<const u32x4*>(Ks + KSWZ(r32, cb) + 16);
;     const u32x4 c0 = *reinterpret_cast<const u32x4*>(Ks + KSWZ(32 + r32, cb)), c1 = *reinterpret_cast<const u32x4*>(Ks + KSWZ(32 + r32, cb) + 16);
;     const i32x8 b0 = {(int)a0.x, (int)a0.y, (int)a0.z, (int)a0.w, (int)a1.x, (int)a1.y, (int)a1.z, (int)a1.w};
;     const i32x8 b1 = {(int)c0.x, (int)c0.y, (int)c0.z, (int)c0.w, (int)c1.x, (int)c1.y, (int)c1.z, (int)c1.w};
;     p0 = __builtin_amdgcn_mfma_scale_f32_32x32x64_f8f6f4(b0, qr[m], p0, 0, 0, 0, 0x7F7F7F7F, 0, 0x7F7F7F7F);
;     p1 = __builtin_amdgcn_mfma_scale_f32_32x32x64_f8f6f4(b1, qr[m], p1, 0, 0, 0, 0x7F7F7F7F, 0, 0x7F7F7F7F); }
; }
; __device__ __forceinline__ void pv_d0(f32x16* o, const unsigned char* Vs, const i32x8& pa, int r32, int hi) {
; #pragma unroll
;   for (int d0 = 0; d0 < 4; ++d0) { const unsigned char* vp = Vs + (32 * d0 + r32) * 80 + hi * 32;
;     const u32x4 a0 = *reinterpret_cast<const u32x4*>(vp), a1 = *reinterpret_cast<const u32x4*>(vp + 16);
;     const i32x8 vb = {(int)a0.x, (int)a0.y, (int)a0.z, (int)a0.w, (int)a1.x, (int)a1.y, (int)a1.z, (int)a1.w};
;     o[d0] = __builtin_amdgcn_mfma_scale_f32_32x32x64_f8f6f4(pa, vb, o[d0], 0, 0, 0, 0x7A7A7A7A, 0, 0x7F7F7F7F); }
; __device__ __forceinline__ void attn_body(const unsigned char* __restrict__ Qb, const unsigned char* __restrict__ Kh, const unsigned char* __restrict__ Vt,
;                                           bf16_t* __restrict__ Ob, int seq, char* lds) {
;     ...
;   f32x16 pA0, pA1, pB0, pB1; float mnA, mnB, alA, alB; i32x8 pa; const int NT = seq / KVBLK;
.Latt_loop:
	s_and_b32 s0, s6, 3
	s_mul_i32 s0, s0, 13312
	v_add_u32_e32 v229, s0, v220
	s_add_u32 s0, s6, 1
	s_and_b32 s0, s0, 3
	s_mul_i32 s0, s0, 13312
	v_add_u32_e32 v225, s0, v220
	s_cmp_eq_u32 s6, 0
	s_cbranch_scc1 .Latt_m_first
	s_add_u32 s0, s6, 3
	s_and_b32 s0, s0, 3
	s_mul_i32 s0, s0, 10240
	v_add_u32_e32 v224, s0, v221
	s_add_u32 s4, s6, 2
	s_and_b32 s0, s4, 3
	s_mul_i32 s1, s0, 10240
	s_mul_i32 s5, s0, 13312
	ds_read_b128 v[176:179], v224 offset:0
	ds_read_b128 v[180:183], v224 offset:16
	ds_read_b128 v[184:187], v224 offset:2560
	ds_read_b128 v[188:191], v224 offset:2576
	s_waitcnt lgkmcnt(4)
	v_mfma_scale_f32_32x32x64_f8f6f4 v[64:79], v[128:135], v[96:103], v[160:175], v235, v201 op_sel_hi:[0,0,0]
	ds_read_b128 v[128:131], v229 offset:41088
	ds_read_b128 v[132:135], v229 offset:41104
	v_mfma_scale_f32_32x32x64_f8f6f4 v[80:95], v[136:143], v[96:103], v[160:175], v235, v201 op_sel_hi:[0,0,0]
	ds_read_b128 v[136:139], v229 offset:47744
	ds_read_b128 v[140:143], v229 offset:47760
	s_cmp_lt_u32 s4, 128
	s_cbranch_scc0 .Latt_ms_nowr
	v_add_u32_e32 v228, s1, v217
	v_add_u32_e32 v226, s5, v218
	s_waitcnt vmcnt(0)
	ds_write2_b32 v228, v202, v204 offset1:1
	ds_write2_b32 v228, v203, v205 offset0:8 offset1:9
	ds_write_b128 v226, v[206:209] offset:40960
	s_cmp_lt_u32 s12, 4
	s_cbranch_scc0 .Latt_ms_w1
	v_add_u32_e32 v231, s5, v219
	ds_write_b128 v231, v[210:213] offset:40960

; __device__ __forceinline__ void partialSM(f32x16& p0, f32x16& p1, float& m_reg, float& mn, float& alpha) {
;   constexpr float C = SCALE * 1.4426950408889634f;
;   float pmax = p0[0]; for (int r = 1; r < 16; ++r) pmax = fmaxf(pmax, p0[r]); for (int r = 0; r < 16; ++r) pmax = fmaxf(pmax, p1[r]);
;   { auto rr = __builtin_amdgcn_permlane32_swap(__float_as_uint(pmax), __float_as_uint(pmax), false, false);
;     pmax = fmaxf(__uint_as_float(rr[0]), __uint_as_float(rr[1])); }
;   if (__builtin_expect(__all(pmax - m_reg <= THR / SCALE), 1)) { mn = m_reg; alpha = 1.f; }
;   else { mn = fmaxf(m_reg, pmax); alpha = __builtin_amdgcn_exp2f((m_reg - mn) * C); m_reg = mn; }
.Latt_m_nobar:
	v_max3_f32 v228, v64, v65, v66
	v_max3_f32 v229, v80, v81, v82
	v_max3_f32 v228, v228, v67, v68
	v_max3_f32 v229, v229, v83, v84
	v_max3_f32 v228, v228, v69, v70
	v_max3_f32 v229, v229, v85, v86
	v_max3_f32 v228, v228, v71, v72
	v_max3_f32 v229, v229, v87, v88
	v_max3_f32 v228, v228, v73, v74
	v_max3_f32 v229, v229, v89, v90
	v_max3_f32 v228, v228, v75, v76
	v_max3_f32 v229, v229, v91, v92
	v_max3_f32 v228, v228, v77, v78
	v_max3_f32 v229, v229, v93, v94
	v_max3_f32 v228, v228, v79, v95
	v_max_f32_e32 v228, v228, v229
	v_mov_b32_e32 v229, v228
	s_nop 1
	v_permlane32_swap_b32_e32 v228, v229
	v_max_f32_e32 v228, v228, v229
	v_cmp_ge_f32_e32 vcc, s13, v228
	v_mov_b32_e32 v226, 1.0
	s_cmp_eq_u32 s6, 0
	s_cbranch_scc1 .Latt_rare
	s_cmp_eq_u64 vcc, exec
	s_cbranch_scc0 .Latt_rare

; __device__ __forceinline__ bf16_t f2bf(float f) { return (bf16_t)(cvt_pk_bf16(f, 0.f) & 0xffffu); }
; #define SBAR() __builtin_amdgcn_sched_barrier(0)
; __device__ __forceinline__ int crow(int r, int hi) { return (r & 3) + 8 * (r >> 2) + 4 * hi; }
; __device__ __forceinline__ void attn_body(const unsigned char* __restrict__ Qb, const unsigned char* __restrict__ Kh, const unsigned char* __restrict__ Vt,
;                                           bf16_t* __restrict__ Ob, int seq, char* lds) {
;     ...
;   STEP(NT - 1, pB0, pB1, mnB, alB, pA0, pA1, alA);
;   finishSM(pB0, pB1, alB, l_reg, pa); SBAR();
;   pv_d0(o, V_lds + sP * SHM_V, pa, r32, hi);
;     ...
;   if (hi == 0) li_l[r32] = l_reg; asm volatile("s_waitcnt lgkmcnt(0)" ::: "memory");
;   float rli[16];
; #pragma unroll
;   for (int r = 0; r < 16; ++r) rli[r] = 32.f * __builtin_amdgcn_rcpf(li_l[crow(r, hi)]);
;   bf16_t* Ow = Ob + (long)(wid * QBLK) * LDO;
; #pragma unroll
;   for (int r = 0; r < 16; ++r) { int orow = crow(r, hi);
;     for (int d0 = 0; d0 < 4; ++d0) Ow[(long)orow * LDO + d0 * 32 + r32] = f2bf(o[d0][r] * rli[r]); }
.Latt_v_nobar:
	s_add_u32 s6, s6, 1
	s_cmp_lt_u32 s6, 128
	s_cbranch_scc1 .Latt_loop
.Latt_tail:
	s_mov_b32 s0, 30720
	v_add_u32_e32 v224, s0, v221
	ds_read_b128 v[176:179], v224 offset:0
	ds_read_b128 v[180:183], v224 offset:16
	ds_read_b128 v[184:187], v224 offset:2560
	ds_read_b128 v[188:191], v224 offset:2576
	s_waitcnt lgkmcnt(2)
	v_mfma_scale_f32_32x32x64_f8f6f4 v[0:15], v[120:127], v[176:183], v[0:15], v237, v235 op_sel_hi:[0,0,0]
	ds_read_b128 v[176:179], v224 offset:5120
	ds_read_b128 v[180:183], v224 offset:5136
	s_waitcnt lgkmcnt(2)
	v_mfma_scale_f32_32x32x64_f8f6f4 v[16:31], v[120:127], v[184:191], v[16:31], v237, v235 op_sel_hi:[0,0,0]
	ds_read_b128 v[184:187], v224 offset:7680
	ds_read_b128 v[188:191], v224 offset:7696
	s_waitcnt lgkmcnt(2)
	v_mfma_scale_f32_32x32x64_f8f6f4 v[32:47], v[120:127], v[176:183], v[32:47], v237, v235 op_sel_hi:[0,0,0]
	s_waitcnt lgkmcnt(0)
	v_mfma_scale_f32_32x32x64_f8f6f4 v[48:63], v[120:127], v[184:191], v[48:63], v237, v235 op_sel_hi:[0,0,0]
	s_mov_b32 exec_hi, 0
	ds_write_b32 v222, v194
	s_mov_b64 exec, -1
	s_waitcnt lgkmcnt(0)
	ds_read_b128 v[64:67], v223 offset:0
	ds_read_b128 v[68:71], v223 offset:32
	ds_read_b128 v[72:75], v223 offset:64
	ds_read_b128 v[76:79], v223 offset:96
	v_lshrrev_b32_e32 v231, 6, v192
	v_bfe_u32 v229, v192, 5, 1
	v_lshl_add_u32 v231, v231, 3, v229
	v_and_b32_e32 v201, 31, v192
	v_lshlrev_b32_e32 v231, 14, v231
	v_lshl_add_u32 v225, v201, 1, v231
	s_waitcnt lgkmcnt(0)
	v_rcp_f32_e32 v64, v64
	v_rcp_f32_e32 v65, v65
	v_rcp_f32_e32 v66, v66
	v_rcp_f32_e32 v67, v67
	v_rcp_f32_e32 v68, v68
	v_rcp_f32_e32 v69, v69
	v_rcp_f32_e32 v70, v70
	v_rcp_f32_e32 v71, v71
	v_rcp_f32_e32 v72, v72
	v_rcp_f32_e32 v73, v73
	v_rcp_f32_e32 v74, v74
	v_rcp_f32_e32 v75, v75
	v_rcp_f32_e32 v76, v76
	v_rcp_f32_e32 v77, v77
	v_rcp_f32_e32 v78, v78
	v_rcp_f32_e32 v79, v79
	s_nop 0
	v_mul_f32_e32 v64, 0x42000000, v64
	v_mul_f32_e32 v65, 0x42000000, v65
	v_mul_f32_e32 v66, 0x42000000, v66
	v_mul_f32_e32 v67, 0x42000000, v67
	v_mul_f32_e32 v68, 0x42000000, v68
	v_mul_f32_e32 v69, 0x42000000, v69
	v_mul_f32_e32 v70, 0x42000000, v70
	v_mul_f32_e32 v71, 0x42000000, v71
	v_mul_f32_e32 v72, 0x42000000, v72
	v_mul_f32_e32 v73, 0x42000000, v73
	v_mul_f32_e32 v74, 0x42000000, v74
	v_mul_f32_e32 v75, 0x42000000, v75
	v_mul_f32_e32 v76, 0x42000000, v76
	v_mul_f32_e32 v77, 0x42000000, v77
	v_mul_f32_e32 v78, 0x42000000, v78
	v_mul_f32_e32 v79, 0x42000000, v79
	s_nop 7
	v_mul_f32_e32 v80, v0, v64
	v_cvt_pk_bf16_f32 v80, v80, v195
	v_mul_f32_e32 v81, v16, v64
	v_cvt_pk_bf16_f32 v81, v81, v195
	v_mul_f32_e32 v82, v32, v64
	v_cvt_pk_bf16_f32 v82, v82, v195
	v_mul_f32_e32 v83, v48, v64
	v_cvt_pk_bf16_f32 v83, v83, v195
	global_store_short v225, v80, s[16:17] offset:0
	global_store_short v225, v81, s[16:17] offset:64
	global_store_short v225, v82, s[16:17] offset:128
	global_store_short v225, v83, s[16:17] offset:192
	v_add_u32_e32 v224, 0x1000, v225
	v_mul_f32_e32 v80, v1, v65
	v_cvt_pk_bf16_f32 v80, v80, v195
	v_mul_f32_e32 v81, v17, v65
	v_cvt_pk_bf16_f32 v81, v81, v195
	v_mul_f32_e32 v82, v33, v65
	v_cvt_pk_bf16_f32 v82, v82, v195
	v_mul_f32_e32 v83, v49, v65
	v_cvt_pk_bf16_f32 v83, v83, v195
	global_store_short v224, v80, s[16:17] offset:0
	global_store_short v224, v81, s[16:17] offset:64
	global_store_short v224, v82, s[16:17] offset:128
	global_store_short v224, v83, s[16:17] offset:192
	v_add_u32_e32 v224, 0x2000, v225
	v_mul_f32_e32 v80, v2, v66
	v_cvt_pk_bf16_f32 v80, v80, v195
	v_mul_f32_e32 v81, v18, v66
	v_cvt_pk_bf16_f32 v81, v81, v195
	v_mul_f32_e32 v82, v34, v66
	v_cvt_pk_bf16_f32 v82, v82, v195
	v_mul_f32_e32 v83, v50, v66
	v_cvt_pk_bf16_f32 v83, v83, v195
	global_store_short v224, v80, s[16:17] offset:0
	global_store_short v224, v81, s[16:17] offset:64
	global_store_short v224, v82, s[16:17] offset:128
	global_store_short v224, v83, s[16:17] offset:192
	v_add_u32_e32 v224, 0x3000, v225
	v_mul_f32_e32 v80, v3, v67
	v_cvt_pk_bf16_f32 v80, v80, v195
	v_mul_f32_e32 v81, v19, v67
	v_cvt_pk_bf16_f32 v81, v81, v195
	v_mul_f32_e32 v82, v35, v67
	v_cvt_pk_bf16_f32 v82, v82, v195
	v_mul_f32_e32 v83, v51, v67
	v_cvt_pk_bf16_f32 v83, v83, v195
	global_store_short v224, v80, s[16:17] offset:0
	global_store_short v224, v81, s[16:17] offset:64
	global_store_short v224, v82, s[16:17] offset:128
	global_store_short v224, v83, s[16:17] offset:192
	v_add_u32_e32 v224, 0x8000, v225
	v_mul_f32_e32 v80, v4, v68
	v_cvt_pk_bf16_f32 v80, v80, v195
	v_mul_f32_e32 v81, v20, v68
	v_cvt_pk_bf16_f32 v81, v81, v195
	v_mul_f32_e32 v82, v36, v68
	v_cvt_pk_bf16_f32 v82, v82, v195
	v_mul_f32_e32 v83, v52, v68
	v_cvt_pk_bf16_f32 v83, v83, v195
	global_store_short v224, v80, s[16:17] offset:0
	global_store_short v224, v81, s[16:17] offset:64
	global_store_short v224, v82, s[16:17] offset:128
	global_store_short v224, v83, s[16:17] offset:192
	v_add_u32_e32 v224, 0x9000, v225
	v_mul_f32_e32 v80, v5, v69
	v_cvt_pk_bf16_f32 v80, v80, v195
	v_mul_f32_e32 v81, v21, v69
	v_cvt_pk_bf16_f32 v81, v81, v195
	v_mul_f32_e32 v82, v37, v69
	v_cvt_pk_bf16_f32 v82, v82, v195
	v_mul_f32_e32 v83, v53, v69
	v_cvt_pk_bf16_f32 v83, v83, v195
	global_store_short v224, v80, s[16:17] offset:0
	global_store_short v224, v81, s[16:17] offset:64
; __device__ __forceinline__ bf16_t f2bf(float f) { return (bf16_t)(cvt_pk_bf16(f, 0.f) & 0xffffu); }
; __device__ __forceinline__ int crow(int r, int hi) { return (r & 3) + 8 * (r >> 2) + 4 * hi; }
; __device__ __forceinline__ void attn_body(const unsigned char* __restrict__ Qb, const unsigned char* __restrict__ Kh, const unsigned char* __restrict__ Vt,
;                                           bf16_t* __restrict__ Ob, int seq, char* lds) {
;     ...
;   for (int r = 0; r < 16; ++r) { int orow = crow(r, hi);
;     for (int d0 = 0; d0 < 4; ++d0) Ow[(long)orow * LDO + d0 * 32 + r32] = f2bf(o[d0][r] * rli[r]); }
;   asm volatile("s_waitcnt vmcnt(0)" ::: "memory");
;   __syncthreads();
; __global__ void __launch_bounds__(512) mega_fwd(Params p) {
;     ...
;             for (int it = bx; it < 256; it += G) { const int h = it & 7, qb = it >> 3;
;                 att::attn_body((const unsigned char*)B.Q + ((size_t)h * S_ + qb * 256) * 192, (const unsigned char*)B.K + (size_t)h * S_ * 192, (const unsigned char*)B.V + (size_t)h * 128 * S_,
;                                B.Y + (size_t)(qb * 256) * DM + 1024 + h * 128, S_, (char*)lds_raw); }
	global_store_short v224, v82, s[16:17] offset:128
	global_store_short v224, v83, s[16:17] offset:192
	v_add_u32_e32 v224, 0xa000, v225
	v_mul_f32_e32 v80, v6, v70
	v_cvt_pk_bf16_f32 v80, v80, v195
	v_mul_f32_e32 v81, v22, v70
	v_cvt_pk_bf16_f32 v81, v81, v195
	v_mul_f32_e32 v82, v38, v70
	v_cvt_pk_bf16_f32 v82, v82, v195
	v_mul_f32_e32 v83, v54, v70
	v_cvt_pk_bf16_f32 v83, v83, v195
	global_store_short v224, v80, s[16:17] offset:0
	global_store_short v224, v81, s[16:17] offset:64
	global_store_short v224, v82, s[16:17] offset:128
	global_store_short v224, v83, s[16:17] offset:192
	v_add_u32_e32 v224, 0xb000, v225
	v_mul_f32_e32 v80, v7, v71
	v_cvt_pk_bf16_f32 v80, v80, v195
	v_mul_f32_e32 v81, v23, v71
	v_cvt_pk_bf16_f32 v81, v81, v195
	v_mul_f32_e32 v82, v39, v71
	v_cvt_pk_bf16_f32 v82, v82, v195
	v_mul_f32_e32 v83, v55, v71
	v_cvt_pk_bf16_f32 v83, v83, v195
	global_store_short v224, v80, s[16:17] offset:0
	global_store_short v224, v81, s[16:17] offset:64
	global_store_short v224, v82, s[16:17] offset:128
	global_store_short v224, v83, s[16:17] offset:192
	v_add_u32_e32 v224, 0x10000, v225
	v_mul_f32_e32 v80, v8, v72
	v_cvt_pk_bf16_f32 v80, v80, v195
	v_mul_f32_e32 v81, v24, v72
	v_cvt_pk_bf16_f32 v81, v81, v195
	v_mul_f32_e32 v82, v40, v72
	v_cvt_pk_bf16_f32 v82, v82, v195
	v_mul_f32_e32 v83, v56, v72
	v_cvt_pk_bf16_f32 v83, v83, v195
	global_store_short v224, v80, s[16:17] offset:0
	global_store_short v224, v81, s[16:17] offset:64
	global_store_short v224, v82, s[16:17] offset:128
	global_store_short v224, v83, s[16:17] offset:192
	v_add_u32_e32 v224, 0x11000, v225
	v_mul_f32_e32 v80, v9, v73
	v_cvt_pk_bf16_f32 v80, v80, v195
	v_mul_f32_e32 v81, v25, v73
	v_cvt_pk_bf16_f32 v81, v81, v195
	v_mul_f32_e32 v82, v41, v73
	v_cvt_pk_bf16_f32 v82, v82, v195
	v_mul_f32_e32 v83, v57, v73
	v_cvt_pk_bf16_f32 v83, v83, v195
	global_store_short v224, v80, s[16:17] offset:0
	global_store_short v224, v81, s[16:17] offset:64
	global_store_short v224, v82, s[16:17] offset:128
	global_store_short v224, v83, s[16:17] offset:192
	v_add_u32_e32 v224, 0x12000, v225
	v_mul_f32_e32 v80, v10, v74
	v_cvt_pk_bf16_f32 v80, v80, v195
	v_mul_f32_e32 v81, v26, v74
	v_cvt_pk_bf16_f32 v81, v81, v195
	v_mul_f32_e32 v82, v42, v74
	v_cvt_pk_bf16_f32 v82, v82, v195
	v_mul_f32_e32 v83, v58, v74
	v_cvt_pk_bf16_f32 v83, v83, v195
	global_store_short v224, v80, s[16:17] offset:0
	global_store_short v224, v81, s[16:17] offset:64
	global_store_short v224, v82, s[16:17] offset:128
	global_store_short v224, v83, s[16:17] offset:192
	v_add_u32_e32 v224, 0x13000, v225
	v_mul_f32_e32 v80, v11, v75
	v_cvt_pk_bf16_f32 v80, v80, v195
	v_mul_f32_e32 v81, v27, v75
	v_cvt_pk_bf16_f32 v81, v81, v195
	v_mul_f32_e32 v82, v43, v75
	v_cvt_pk_bf16_f32 v82, v82, v195
	v_mul_f32_e32 v83, v59, v75
	v_cvt_pk_bf16_f32 v83, v83, v195
	global_store_short v224, v80, s[16:17] offset:0
	global_store_short v224, v81, s[16:17] offset:64
	global_store_short v224, v82, s[16:17] offset:128
	global_store_short v224, v83, s[16:17] offset:192
	v_add_u32_e32 v224, 0x18000, v225
	v_mul_f32_e32 v80, v12, v76
	v_cvt_pk_bf16_f32 v80, v80, v195
	v_mul_f32_e32 v81, v28, v76
	v_cvt_pk_bf16_f32 v81, v81, v195
	v_mul_f32_e32 v82, v44, v76
	v_cvt_pk_bf16_f32 v82, v82, v195
	v_mul_f32_e32 v83, v60, v76
	v_cvt_pk_bf16_f32 v83, v83, v195
	global_store_short v224, v80, s[16:17] offset:0
	global_store_short v224, v81, s[16:17] offset:64
	global_store_short v224, v82, s[16:17] offset:128
	global_store_short v224, v83, s[16:17] offset:192
	v_add_u32_e32 v224, 0x19000, v225
	v_mul_f32_e32 v80, v13, v77
	v_cvt_pk_bf16_f32 v80, v80, v195
	v_mul_f32_e32 v81, v29, v77
	v_cvt_pk_bf16_f32 v81, v81, v195
	v_mul_f32_e32 v82, v45, v77
	v_cvt_pk_bf16_f32 v82, v82, v195
	v_mul_f32_e32 v83, v61, v77
	v_cvt_pk_bf16_f32 v83, v83, v195
	global_store_short v224, v80, s[16:17] offset:0
	global_store_short v224, v81, s[16:17] offset:64
	global_store_short v224, v82, s[16:17] offset:128
	global_store_short v224, v83, s[16:17] offset:192
	v_add_u32_e32 v224, 0x1a000, v225
	v_mul_f32_e32 v80, v14, v78
	v_cvt_pk_bf16_f32 v80, v80, v195
	v_mul_f32_e32 v81, v30, v78
	v_cvt_pk_bf16_f32 v81, v81, v195
	v_mul_f32_e32 v82, v46, v78
	v_cvt_pk_bf16_f32 v82, v82, v195
	v_mul_f32_e32 v83, v62, v78
	v_cvt_pk_bf16_f32 v83, v83, v195
	global_store_short v224, v80, s[16:17] offset:0
	global_store_short v224, v81, s[16:17] offset:64
	global_store_short v224, v82, s[16:17] offset:128
	global_store_short v224, v83, s[16:17] offset:192
	v_add_u32_e32 v224, 0x1b000, v225
	v_mul_f32_e32 v80, v15, v79
	v_cvt_pk_bf16_f32 v80, v80, v195
	v_mul_f32_e32 v81, v31, v79
	v_cvt_pk_bf16_f32 v81, v81, v195
	v_mul_f32_e32 v82, v47, v79
	v_cvt_pk_bf16_f32 v82, v82, v195
	v_mul_f32_e32 v83, v63, v79
	v_cvt_pk_bf16_f32 v83, v83, v195
	global_store_short v224, v80, s[16:17] offset:0
	global_store_short v224, v81, s[16:17] offset:64
	global_store_short v224, v82, s[16:17] offset:128
	global_store_short v224, v83, s[16:17] offset:192
	s_waitcnt vmcnt(0)
	v_readlane_b32 s0, v252, 9
	s_nop 1
	s_add_i32 s25, s25, s0
	s_add_i32 s24, s24, s0
	s_cmpk_gt_i32 s25, 0xff
	s_waitcnt lgkmcnt(0)
	s_barrier
	v_readlane_b32 s1, v252, 10
	s_cbranch_scc1 .LBB0_297
	s_branch .LBB0_260
